# scan recurrence loop rewritten by hand: 445 instead of 550 instructions per 16 steps (one wait per pair, batched output reductions, packed dots)
# speedup vs baseline: 1.0248x; 1.0248x over previous
; __device__ __forceinline__ void scan_phase(const Params& P, LAS unsigned char* lds, int tid, int wid, int lane) {
;     constexpr int NCK = (LPOS + TC - 1) / TC;
;     typedef float f32x2v __attribute__((ext_vector_type(2)));
;     const int vcu_ = (gridDim.x % 8 == 0) ? ((int)blockIdx.x % 8) * ((int)gridDim.x / 8) + (int)blockIdx.x / 8 : (int)blockIdx.x;
;     for (int it = vcu_; it < 256; it += gridDim.x) {
;         const int bh = it >> 2, rg = it & 3, b = bh >> 3, h = bh & 7;
;         f32x4 S = (f32x4){0.f, 0.f, 0.f, 0.f};
;         const int jq = lane & 15, il = 4 * wid + (lane >> 4), ll = tid - 256;
;         ScanRegs R;
;         SC_BAR();
;         if (wid >= 4) { scan_gload(P, R, b, h, rg, 0, ll); scan_cvt_write(P, h, R, lds, ll); scan_gload(P, R, b, h, rg, 1, ll); }
;         SC_BAR();
;         for (int ck = 0; ck < NCK; ++ck) {
;             const int nsteps = (LPOS - TC * ck) < TC ? (LPOS - TC * ck) : TC;
;             if (wid >= 4) {
;                 if (ck + 1 < NCK) { scan_cvt_write(P, h, R, lds + ((ck + 1) & 1) * SBUF, ll); scan_gload(P, R, b, h, rg, ck + 2 < NCK ? ck + 2 : NCK - 1, ll); }
;                 if (ck > 0) scan_flush(P, lds + YOFF + ((ck - 1) & 1) * 2048, b, h, rg, ck - 1, ll);
;             } else {
;                 const LAS unsigned char* buf = lds + (ck & 1) * SBUF + jq * 16; const LAS unsigned char* vbuf = lds + (ck & 1) * SBUF + 1280 + il * 4; const LAS unsigned char* sbuf = lds + (ck & 1) * SBUF + 1600;
;                 LAS float* yb = (LAS float*)(lds + YOFF + (ck & 1) * 2048);
;                 f32x4 w0[2], kh0[2], kk0[2], b0[2], r0[2], wk0[2], w1[2], kh1[2], b1[2], r1[2]; float v0[2], v1[2]; f32x2v bk[2];
;     ...
;                 SC_LOADP(0, 0);
;                 for (int t0 = 0; t0 < nsteps; t0 += 16) {
;                     float ykeep = 0.f;
; #pragma unroll
;                     for (int u = 0; u < 8; ++u) {
;                         SC_LOADP((u + 1) & 1, t0 + 2 * u + 2);
;                         const int s = u & 1;
;                         float dA = dot4(S, kk0[s]), dB = dot4(S, wk0[s]);
;                         dA = row16_allsum(dA); dB = row16_allsum(dB);
;                         const float sa0 = -dA;
;                         const f32x4 S0 = S * w0[s] + (b0[s] * sa0 + kh0[s] * v0[s]);
;                         const float sa1 = -(dB + sa0 * bk[s].x + v0[s] * bk[s].y);
.LBB0_833:
	s_cmp_gt_i32 s88, 8
	s_cselect_b64 s[0:1], -1, 0
	s_cmp_lt_i32 s89, 9
	s_cselect_b64 s[2:3], -1, 0
	s_or_b64 s[0:1], s[0:1], s[2:3]
	s_and_b64 vcc, exec, s[0:1]
	s_cbranch_vccnz .LBB0_938
	s_ashr_i32 s2, s33, 31
	s_lshr_b32 s2, s2, 29
	s_add_i32 s2, s33, s2
	s_and_b32 s3, s2, -8
	s_ashr_i32 s1, s96, 3
	s_sub_i32 s3, s33, s3
	s_mul_i32 s1, s1, s3
	s_ashr_i32 s2, s2, 3
	v_writelane_b32 v254, s91, 27
	s_and_b32 s0, s96, 7
	s_add_i32 s1, s1, s2
	v_writelane_b32 v254, s90, 28
	s_cmp_eq_u32 s0, 0
	v_writelane_b32 v254, s65, 29
	s_cselect_b32 s16, s1, s33
	v_writelane_b32 v254, s66, 30
	s_cmpk_gt_i32 s16, 0xff
	s_mov_b32 s1, 0
	v_writelane_b32 v254, s67, 31
	s_cbranch_scc1 .LBB0_884
	s_waitcnt lgkmcnt(0)
	v_add_u32_e32 v1, 0xffffff00, v209
	v_ashrrev_i32_e32 v2, 3, v1
	v_and_b32_e32 v107, -2, v2
	v_add_u32_e32 v5, -1, v107
	v_cmp_gt_u32_e64 s[8:9], 16, v5
	v_min_u32_e32 v113, 0x80f, v5
	v_add_u32_e32 v5, 31, v107
	v_writelane_b32 v254, s8, 32
	v_lshlrev_b32_e32 v3, 2, v1
	s_movk_i32 s0, 0x650
	v_writelane_b32 v254, s9, 33
	v_cmp_gt_u32_e64 s[8:9], 16, v2
	v_ashrrev_i32_e32 v122, 2, v1
	v_lshlrev_b32_e32 v1, 4, v1
	v_writelane_b32 v254, s8, 34
	v_and_b32_e32 v46, 60, v3
	v_or_b32_e32 v4, 1, v2
	v_writelane_b32 v254, s9, 35
	v_cmp_gt_i32_e64 s[8:9], 15, v107
	v_cmp_lt_i32_e64 s[6:7], 1, v2
	v_cmp_lt_i32_e64 s[10:11], -1, v2
	v_writelane_b32 v254, s8, 36
	v_and_b32_e32 v2, 12, v3
	v_mad_i32_i24 v121, v107, s0, 0
	v_writelane_b32 v254, s9, 37
	s_movk_i32 s8, 0x180
	v_cmp_gt_u32_e64 s[22:23], s8, v209
	v_cmp_gt_u32_e64 s[8:9], 16, v5
	v_mad_i32_i24 v3, v122, s0, 0
	v_and_b32_e32 v124, 48, v1
	v_add_u32_e32 v1, 32, v107
	s_movk_i32 s0, 0xffe0
	v_writelane_b32 v254, s8, 38
	v_cmp_lt_i32_e64 s[28:29], s0, v107
	s_movk_i32 s0, 0xffdf
	v_writelane_b32 v254, s9, 39
	v_cmp_gt_u32_e64 s[8:9], 16, v1
	v_cmp_lt_i32_e64 s[34:35], s0, v107
	s_movk_i32 s0, 0xffde
	v_writelane_b32 v254, s8, 40
	v_min_i32_e32 v125, 0x80f, v1
	v_min_u32_e32 v129, 0x80f, v1
	v_writelane_b32 v254, s9, 41
	v_cmp_lt_i32_e64 s[38:39], s0, v107
	s_movk_i32 s0, 0xffef
	v_lshrrev_b32_e32 v1, 2, v208
	s_cmpk_gt_u32 s92, 0xff
	v_cmp_gt_i32_e64 s[40:41], s0, v107
	v_and_b32_e32 v1, 12, v1
	v_readlane_b32 s0, v254, 27
	s_cselect_b64 s[72:73], -1, 0
	v_and_b32_e32 v47, 15, v209
	v_lshl_or_b32 v134, s0, 4, v1
	s_add_i32 s0, 0, 0x19400
	v_mov_b32_e32 v0, 0
	s_add_u32 s74, s86, 0x4d00000
	v_lshlrev_b32_e32 v48, 4, v47
	v_mov_b32_e32 v49, v0
	s_addc_u32 s75, s87, 0
	v_lshl_add_u64 v[50:51], s[76:77], 0, v[48:49]
	s_add_u32 s76, s86, 0xc740000
	s_addc_u32 s77, s87, 0
	s_add_u32 s78, s86, 0xd780000
	s_addc_u32 s79, s87, 0
	s_add_u32 s80, s86, 0xe7c0000
	v_min_i32_e32 v112, 0x80f, v4
	v_cmp_gt_i32_e64 s[4:5], 16, v4
	v_min_u32_e32 v117, 0x80f, v4
	v_add_u32_e32 v4, 33, v107
	v_and_b32_e32 v1, 3, v209
	s_addc_u32 s81, s87, 0
	v_min_i32_e32 v126, 0x80f, v4
	v_cmp_gt_i32_e64 s[26:27], 16, v4
	v_min_u32_e32 v127, 0x80f, v5
	v_min_u32_e32 v131, 0x80f, v4
	v_lshlrev_b32_e32 v4, 6, v122
	v_lshlrev_b32_e32 v5, 4, v1
	s_add_u32 s82, s86, 0x5d40000
	v_add_u32_e32 v135, s0, v134
	v_add3_u32 v137, s0, v4, v5
	v_lshlrev_b32_e32 v4, 2, v1
	v_add_u32_e32 v1, -16, v122
	s_movk_i32 s0, 0xf7ff
	v_lshlrev_b32_e32 v6, 1, v46
	v_mov_b32_e32 v7, v0
	s_addc_u32 s83, s87, 0
	v_cmp_lt_u32_e32 vcc, s0, v1
	v_lshl_add_u64 v[8:9], s[86:87], 0, v[6:7]
	s_mov_b64 s[8:9], 0x7dc0000
	s_add_u32 s92, s86, 0xb700000
	v_min_u32_e32 v115, 0x80f, v107
	v_bfe_u32 v119, v209, 2, 5
	v_lshl_add_u64 v[52:53], v[8:9], 0, s[8:9]
	s_addc_u32 s93, s87, 0
	s_and_b64 s[8:9], s[72:73], vcc
	v_min_i32_e32 v109, 0x80f, v107
	v_cmp_gt_i32_e64 s[2:3], 16, v107
	v_or_b32_e32 v114, 0x4000, v113
	v_or_b32_e32 v116, 0x4000, v115
	v_cmp_lt_i32_e64 s[14:15], -2, v107
	v_or_b32_e32 v118, 0x4000, v117
	v_cmp_gt_u32_e64 s[18:19], 16, v119
	v_mul_i32_i24_e32 v120, 0x650, v107
	v_cmp_eq_u32_e64 s[20:21], 0, v47
	v_mul_i32_i24_e32 v123, 0x650, v122
	v_cmp_gt_i32_e64 s[24:25], -16, v107
	v_or_b32_e32 v128, 0x4000, v127
	v_or_b32_e32 v130, 0x4000, v129
	v_or_b32_e32 v132, 0x4000, v131
	v_or_b32_e32 v133, 32, v119
	v_add_u32_e32 v136, 63, v107
	v_add_u32_e32 v138, 0x7f0, v122
	v_and_b32_e32 v255, 8, v47
	v_cmp_ne_u32_e64 s[42:43], 0, v255
	v_and_b32_e32 v255, 4, v47
	v_cmp_ne_u32_e64 s[44:45], 0, v255
	v_and_b32_e32 v255, 3, v47
	v_cmp_eq_u32_e64 s[46:47], 0, v255
	v_cmp_eq_u32_e64 s[48:49], 1, v255
	v_cmp_eq_u32_e64 s[50:51], 2, v255
	v_cmp_eq_u32_e64 s[52:53], 3, v255
	v_lshlrev_b32_e32 v255, 2, v255
	s_mov_b64 s[98:99], exec
	s_and_b64 exec, s[98:99], s[44:45]
	v_or_b32_e32 v255, 2, v255
	s_and_b64 exec, s[98:99], s[42:43]
	v_or_b32_e32 v255, 1, v255
	s_mov_b64 exec, s[98:99]
	v_lshlrev_b32_e32 v255, 6, v255
	v_cmp_eq_u32_e64 s[54:55], 7, v47
	v_cmp_eq_u32_e64 s[56:57], 8, v47
	v_cmp_eq_u32_e64 s[58:59], 9, v47
	v_cmp_eq_u32_e64 s[60:61], 10, v47
	v_cmp_eq_u32_e64 s[62:63], 11, v47
	v_cmp_eq_u32_e64 s[64:65], 12, v47
	v_cmp_eq_u32_e64 s[66:67], 13, v47
	v_cmp_eq_u32_e64 s[68:69], 14, v47
	v_lshl_add_u64 v[54:55], s[74:75], 0, v[6:7]
	v_lshl_add_u64 v[56:57], s[76:77], 0, v[6:7]
	v_lshl_add_u64 v[58:59], s[78:79], 0, v[6:7]
	v_lshl_add_u64 v[60:61], s[80:81], 0, v[6:7]
	s_and_b64 s[94:95], s[8:9], s[22:23]
	v_add_u32_e32 v49, v3, v124
	v_lshlrev_b32_e32 v62, 1, v2
	v_lshlrev_b32_e32 v64, 1, v4
	v_mov_b32_e32 v139, 0x4000
	v_cmp_eq_u32_e64 s[70:71], 15, v47
	s_branch .LBB0_837

; __device__ __forceinline__ float row16_allsum(float x) { x = ROW_ROR_ADD(x, 8); x = ROW_ROR_ADD(x, 4); x = ROW_ROR_ADD(x, 2); x = ROW_ROR_ADD(x, 1); return x; }
; __device__ __forceinline__ float dot4(f32x4 a, f32x4 b) { return __builtin_fmaf(a[3], b[3], __builtin_fmaf(a[2], b[2], __builtin_fmaf(a[1], b[1], a[0] * b[0]))); }
; __device__ __forceinline__ void scan_phase(const Params& P, LAS unsigned char* lds, int tid, int wid, int lane) {
;     ...
;                 for (int t0 = 0; t0 < nsteps; t0 += 16) {
;                     float ykeep = 0.f;
; #pragma unroll
;                     for (int u = 0; u < 8; ++u) {
;                         SC_LOADP((u + 1) & 1, t0 + 2 * u + 2);
;                         const int s = u & 1;
;                         float dA = dot4(S, kk0[s]), dB = dot4(S, wk0[s]);
;                         dA = row16_allsum(dA); dB = row16_allsum(dB);
;                         const float sa0 = -dA;
;                         const f32x4 S0 = S * w0[s] + (b0[s] * sa0 + kh0[s] * v0[s]);
;                         const float sa1 = -(dB + sa0 * bk[s].x + v0[s] * bk[s].y);
;                         const f32x4 S1 = S0 * w1[s] + (b1[s] * sa1 + kh1[s] * v1[s]);
;                         float y0 = dot4(S0, r0[s]), y1 = dot4(S1, r1[s]);
;                         y0 = row16_allsum(y0); y1 = row16_allsum(y1);
;                         ykeep = (jq == 2 * u) ? y0 : ykeep; ykeep = (jq == 2 * u + 1) ? y1 : ykeep;
;                         S = S1;
;                     }
;                     yb[(t0 + jq) * 16 + il] = ykeep;
.LBB0_881:
	s_mul_i32 vcc_lo, s37, 0x650
	v_add_u32_e32 v140, vcc_lo, v1
	v_add_u32_e32 v141, vcc_lo, v63
	s_add_i32 vcc_lo, s36, vcc_lo
	v_mov_b32_e32 v142, vcc_lo
	ds_read_b128 v[144:147], v140 offset:3232
	ds_read_b128 v[148:151], v140 offset:3488
	ds_read_b128 v[152:155], v140 offset:3744
	ds_read_b128 v[156:159], v140 offset:4000
	ds_read_b128 v[160:163], v140 offset:4256
	ds_read_b128 v[164:167], v140 offset:4576
	ds_read_b128 v[168:171], v140 offset:4848
	ds_read_b128 v[172:175], v140 offset:5104
	ds_read_b128 v[176:179], v140 offset:5616
	ds_read_b128 v[180:183], v140 offset:5872
	ds_read_b32 v184, v141 offset:4512
	ds_read_b32 v186, v141 offset:6128
	ds_read_b64 v[188:189], v142 offset:4832
	s_waitcnt lgkmcnt(13)
	v_pk_mul_f32 v[42:43], v[2:3], v[42:43]
	v_pk_mul_f32 v[38:39], v[2:3], v[38:39]
	v_pk_fma_f32 v[42:43], v[4:5], v[44:45], v[42:43]
	v_pk_fma_f32 v[38:39], v[4:5], v[40:41], v[38:39]
	v_add_f32_e32 v42, v42, v43
	v_add_f32_e32 v38, v38, v39
	v_pk_mul_f32 v[190:191], v[22:23], v[108:109] op_sel_hi:[1,0]
	v_add_f32_dpp v42, v42, v42 row_ror:8 row_mask:0xf bank_mask:0xf bound_ctrl:1
	v_add_f32_dpp v38, v38, v38 row_ror:8 row_mask:0xf bank_mask:0xf bound_ctrl:1
	v_pk_mul_f32 v[192:193], v[24:25], v[108:109] op_sel_hi:[1,0]
	v_add_f32_dpp v42, v42, v42 row_ror:4 row_mask:0xf bank_mask:0xf bound_ctrl:1
	v_add_f32_dpp v38, v38, v38 row_ror:4 row_mask:0xf bank_mask:0xf bound_ctrl:1
	v_pk_mul_f32 v[44:45], v[26:27], v[106:107] op_sel_hi:[1,0]
	v_add_f32_dpp v42, v42, v42 row_ror:2 row_mask:0xf bank_mask:0xf bound_ctrl:1
	v_add_f32_dpp v38, v38, v38 row_ror:2 row_mask:0xf bank_mask:0xf bound_ctrl:1
	v_pk_mul_f32 v[40:41], v[28:29], v[106:107] op_sel_hi:[1,0]
	v_add_f32_dpp v42, v42, v42 row_ror:1 row_mask:0xf bank_mask:0xf bound_ctrl:1
	v_add_f32_dpp v38, v38, v38 row_ror:1 row_mask:0xf bank_mask:0xf bound_ctrl:1
	v_pk_fma_f32 v[190:191], v[34:35], v[42:43], v[190:191] op_sel_hi:[1,0,1] neg_lo:[0,1,0] neg_hi:[0,1,0]
	v_pk_fma_f32 v[192:193], v[36:37], v[42:43], v[192:193] op_sel_hi:[1,0,1] neg_lo:[0,1,0] neg_hi:[0,1,0]
	v_fma_f32 v43, -v42, v110, v38
	v_pk_fma_f32 v[190:191], v[2:3], v[14:15], v[190:191]
	v_pk_fma_f32 v[192:193], v[4:5], v[16:17], v[192:193]
	v_fma_f32 v43, v108, v111, v43
	v_pk_mul_f32 v[6:7], v[190:191], v[6:7]
	v_pk_fma_f32 v[44:45], v[30:31], v[42:43], v[44:45] op_sel:[0,1,0] op_sel_hi:[1,1,1] neg_lo:[0,1,0] neg_hi:[0,1,0]
	v_pk_fma_f32 v[6:7], v[192:193], v[8:9], v[6:7]
	v_pk_fma_f32 v[40:41], v[32:33], v[42:43], v[40:41] op_sel:[0,1,0] op_sel_hi:[1,1,1] neg_lo:[0,1,0] neg_hi:[0,1,0]
	v_add_f32_e32 v185, v6, v7
	v_pk_fma_f32 v[2:3], v[190:191], v[18:19], v[44:45]
	v_pk_fma_f32 v[4:5], v[192:193], v[20:21], v[40:41]
	v_pk_mul_f32 v[10:11], v[2:3], v[10:11]
	v_pk_fma_f32 v[10:11], v[4:5], v[12:13], v[10:11]
	v_add_f32_e32 v187, v10, v11
	ds_read_b128 v[14:17], v140 offset:6464
	ds_read_b128 v[22:25], v140 offset:6720
	ds_read_b128 v[42:45], v140 offset:6976
	ds_read_b128 v[34:37], v140 offset:7232
	ds_read_b128 v[6:9], v140 offset:7488
	ds_read_b128 v[38:41], v140 offset:7808
	ds_read_b128 v[18:21], v140 offset:8080
	ds_read_b128 v[26:29], v140 offset:8336
	ds_read_b128 v[30:33], v140 offset:8848
	ds_read_b128 v[10:13], v140 offset:9104
	ds_read_b32 v108, v141 offset:7744
	ds_read_b32 v106, v141 offset:9360
	ds_read_b64 v[110:111], v142 offset:8064
	s_waitcnt lgkmcnt(13)
	v_pk_mul_f32 v[152:153], v[2:3], v[152:153]
	v_pk_mul_f32 v[164:165], v[2:3], v[164:165]
	v_pk_fma_f32 v[152:153], v[4:5], v[154:155], v[152:153]
	v_pk_fma_f32 v[164:165], v[4:5], v[166:167], v[164:165]
	v_add_f32_e32 v152, v152, v153
	v_add_f32_e32 v164, v164, v165
	v_pk_mul_f32 v[190:191], v[148:149], v[184:185] op_sel_hi:[1,0]
	v_add_f32_dpp v152, v152, v152 row_ror:8 row_mask:0xf bank_mask:0xf bound_ctrl:1
	v_add_f32_dpp v164, v164, v164 row_ror:8 row_mask:0xf bank_mask:0xf bound_ctrl:1
	v_pk_mul_f32 v[192:193], v[150:151], v[184:185] op_sel_hi:[1,0]
	v_add_f32_dpp v152, v152, v152 row_ror:4 row_mask:0xf bank_mask:0xf bound_ctrl:1
	v_add_f32_dpp v164, v164, v164 row_ror:4 row_mask:0xf bank_mask:0xf bound_ctrl:1
	v_pk_mul_f32 v[154:155], v[172:173], v[186:187] op_sel_hi:[1,0]
	v_add_f32_dpp v152, v152, v152 row_ror:2 row_mask:0xf bank_mask:0xf bound_ctrl:1
	v_add_f32_dpp v164, v164, v164 row_ror:2 row_mask:0xf bank_mask:0xf bound_ctrl:1
	v_pk_mul_f32 v[166:167], v[174:175], v[186:187] op_sel_hi:[1,0]
	v_add_f32_dpp v152, v152, v152 row_ror:1 row_mask:0xf bank_mask:0xf bound_ctrl:1
	v_add_f32_dpp v164, v164, v164 row_ror:1 row_mask:0xf bank_mask:0xf bound_ctrl:1
	v_pk_fma_f32 v[190:191], v[156:157], v[152:153], v[190:191] op_sel_hi:[1,0,1] neg_lo:[0,1,0] neg_hi:[0,1,0]
	v_pk_fma_f32 v[192:193], v[158:159], v[152:153], v[192:193] op_sel_hi:[1,0,1] neg_lo:[0,1,0] neg_hi:[0,1,0]
	v_fma_f32 v153, -v152, v188, v164
	v_pk_fma_f32 v[190:191], v[2:3], v[144:145], v[190:191]
	v_pk_fma_f32 v[192:193], v[4:5], v[146:147], v[192:193]
	v_fma_f32 v153, v184, v189, v153
	v_pk_mul_f32 v[160:161], v[190:191], v[160:161]
	v_pk_fma_f32 v[154:155], v[176:177], v[152:153], v[154:155] op_sel:[0,1,0] op_sel_hi:[1,1,1] neg_lo:[0,1,0] neg_hi:[0,1,0]
	v_pk_fma_f32 v[160:161], v[192:193], v[162:163], v[160:161]
	v_pk_fma_f32 v[166:167], v[178:179], v[152:153], v[166:167] op_sel:[0,1,0] op_sel_hi:[1,1,1] neg_lo:[0,1,0] neg_hi:[0,1,0]
	v_add_f32_e32 v107, v160, v161
	v_pk_fma_f32 v[2:3], v[190:191], v[168:169], v[154:155]
	v_pk_fma_f32 v[4:5], v[192:193], v[170:171], v[166:167]
	v_pk_mul_f32 v[180:181], v[2:3], v[180:181]
	v_pk_fma_f32 v[180:181], v[4:5], v[182:183], v[180:181]
	v_add_f32_e32 v109, v180, v181
	v_add_f32_dpp v185, v185, v185 row_ror:8 row_mask:0xf bank_mask:0xf bound_ctrl:1
	v_add_f32_dpp v187, v187, v187 row_ror:8 row_mask:0xf bank_mask:0xf bound_ctrl:1
	v_add_f32_dpp v107, v107, v107 row_ror:8 row_mask:0xf bank_mask:0xf bound_ctrl:1
	v_add_f32_dpp v109, v109, v109 row_ror:8 row_mask:0xf bank_mask:0xf bound_ctrl:1
	v_cndmask_b32_e64 v185, v185, v187, s[42:43]
	v_cndmask_b32_e64 v107, v107, v109, s[42:43]
	ds_read_b128 v[144:147], v140 offset:9696
	ds_read_b128 v[148:151], v140 offset:9952
	ds_read_b128 v[152:155], v140 offset:10208
	ds_read_b128 v[156:159], v140 offset:10464
	ds_read_b128 v[160:163], v140 offset:10720
	ds_read_b128 v[164:167], v140 offset:11040
	ds_read_b128 v[168:171], v140 offset:11312
	ds_read_b128 v[172:175], v140 offset:11568
	ds_read_b128 v[176:179], v140 offset:12080
	ds_read_b128 v[180:183], v140 offset:12336
	ds_read_b32 v184, v141 offset:10976
	ds_read_b32 v186, v141 offset:12592
	ds_read_b64 v[188:189], v142 offset:11296
	v_add_f32_dpp v185, v185, v185 row_half_mirror row_mask:0xf bank_mask:0xf bound_ctrl:1
	v_add_f32_dpp v107, v107, v107 row_half_mirror row_mask:0xf bank_mask:0xf bound_ctrl:1
	s_waitcnt lgkmcnt(13)
; __device__ __forceinline__ float row16_allsum(float x) { x = ROW_ROR_ADD(x, 8); x = ROW_ROR_ADD(x, 4); x = ROW_ROR_ADD(x, 2); x = ROW_ROR_ADD(x, 1); return x; }
; __device__ __forceinline__ float dot4(f32x4 a, f32x4 b) { return __builtin_fmaf(a[3], b[3], __builtin_fmaf(a[2], b[2], __builtin_fmaf(a[1], b[1], a[0] * b[0]))); }
; __device__ __forceinline__ void scan_phase(const Params& P, LAS unsigned char* lds, int tid, int wid, int lane) {
;     ...
;                 for (int t0 = 0; t0 < nsteps; t0 += 16) {
;                     float ykeep = 0.f;
; #pragma unroll
;                     for (int u = 0; u < 8; ++u) {
;                         SC_LOADP((u + 1) & 1, t0 + 2 * u + 2);
;                         const int s = u & 1;
;                         float dA = dot4(S, kk0[s]), dB = dot4(S, wk0[s]);
;                         dA = row16_allsum(dA); dB = row16_allsum(dB);
;                         const float sa0 = -dA;
;                         const f32x4 S0 = S * w0[s] + (b0[s] * sa0 + kh0[s] * v0[s]);
;                         const float sa1 = -(dB + sa0 * bk[s].x + v0[s] * bk[s].y);
;                         const f32x4 S1 = S0 * w1[s] + (b1[s] * sa1 + kh1[s] * v1[s]);
;                         float y0 = dot4(S0, r0[s]), y1 = dot4(S1, r1[s]);
;                         y0 = row16_allsum(y0); y1 = row16_allsum(y1);
;                         ykeep = (jq == 2 * u) ? y0 : ykeep; ykeep = (jq == 2 * u + 1) ? y1 : ykeep;
;                         S = S1;
;                     }
;                     yb[(t0 + jq) * 16 + il] = ykeep;
	v_cndmask_b32_e64 v185, v185, v107, s[44:45]
	v_pk_mul_f32 v[42:43], v[2:3], v[42:43]
	v_pk_mul_f32 v[38:39], v[2:3], v[38:39]
	v_add_f32_dpp v185, v185, v185 quad_perm:[1,0,3,2] row_mask:0xf bank_mask:0xf bound_ctrl:1
	v_pk_fma_f32 v[42:43], v[4:5], v[44:45], v[42:43]
	v_pk_fma_f32 v[38:39], v[4:5], v[40:41], v[38:39]
	v_add_f32_dpp v185, v185, v185 quad_perm:[2,3,0,1] row_mask:0xf bank_mask:0xf bound_ctrl:1
	v_add_f32_e32 v42, v42, v43
	v_add_f32_e32 v38, v38, v39
	v_cndmask_b32_e64 v143, v143, v185, s[46:47]
	v_pk_mul_f32 v[190:191], v[22:23], v[108:109] op_sel_hi:[1,0]
	v_add_f32_dpp v42, v42, v42 row_ror:8 row_mask:0xf bank_mask:0xf bound_ctrl:1
	v_add_f32_dpp v38, v38, v38 row_ror:8 row_mask:0xf bank_mask:0xf bound_ctrl:1
	v_pk_mul_f32 v[192:193], v[24:25], v[108:109] op_sel_hi:[1,0]
	v_add_f32_dpp v42, v42, v42 row_ror:4 row_mask:0xf bank_mask:0xf bound_ctrl:1
	v_add_f32_dpp v38, v38, v38 row_ror:4 row_mask:0xf bank_mask:0xf bound_ctrl:1
	v_pk_mul_f32 v[44:45], v[26:27], v[106:107] op_sel_hi:[1,0]
	v_add_f32_dpp v42, v42, v42 row_ror:2 row_mask:0xf bank_mask:0xf bound_ctrl:1
	v_add_f32_dpp v38, v38, v38 row_ror:2 row_mask:0xf bank_mask:0xf bound_ctrl:1
	v_pk_mul_f32 v[40:41], v[28:29], v[106:107] op_sel_hi:[1,0]
	v_add_f32_dpp v42, v42, v42 row_ror:1 row_mask:0xf bank_mask:0xf bound_ctrl:1
	v_add_f32_dpp v38, v38, v38 row_ror:1 row_mask:0xf bank_mask:0xf bound_ctrl:1
	v_pk_fma_f32 v[190:191], v[34:35], v[42:43], v[190:191] op_sel_hi:[1,0,1] neg_lo:[0,1,0] neg_hi:[0,1,0]
	v_pk_fma_f32 v[192:193], v[36:37], v[42:43], v[192:193] op_sel_hi:[1,0,1] neg_lo:[0,1,0] neg_hi:[0,1,0]
	v_fma_f32 v43, -v42, v110, v38
	v_pk_fma_f32 v[190:191], v[2:3], v[14:15], v[190:191]
	v_pk_fma_f32 v[192:193], v[4:5], v[16:17], v[192:193]
	v_fma_f32 v43, v108, v111, v43
	v_pk_mul_f32 v[6:7], v[190:191], v[6:7]
	v_pk_fma_f32 v[44:45], v[30:31], v[42:43], v[44:45] op_sel:[0,1,0] op_sel_hi:[1,1,1] neg_lo:[0,1,0] neg_hi:[0,1,0]
	v_pk_fma_f32 v[6:7], v[192:193], v[8:9], v[6:7]
	v_pk_fma_f32 v[40:41], v[32:33], v[42:43], v[40:41] op_sel:[0,1,0] op_sel_hi:[1,1,1] neg_lo:[0,1,0] neg_hi:[0,1,0]
	v_add_f32_e32 v185, v6, v7
	v_pk_fma_f32 v[2:3], v[190:191], v[18:19], v[44:45]
	v_pk_fma_f32 v[4:5], v[192:193], v[20:21], v[40:41]
	v_pk_mul_f32 v[10:11], v[2:3], v[10:11]
	v_pk_fma_f32 v[10:11], v[4:5], v[12:13], v[10:11]
	v_add_f32_e32 v187, v10, v11
	ds_read_b128 v[14:17], v140 offset:12928
	ds_read_b128 v[22:25], v140 offset:13184
	ds_read_b128 v[42:45], v140 offset:13440
	ds_read_b128 v[34:37], v140 offset:13696
	ds_read_b128 v[6:9], v140 offset:13952
	ds_read_b128 v[38:41], v140 offset:14272
	ds_read_b128 v[18:21], v140 offset:14544
	ds_read_b128 v[26:29], v140 offset:14800
	ds_read_b128 v[30:33], v140 offset:15312
	ds_read_b128 v[10:13], v140 offset:15568
	ds_read_b32 v108, v141 offset:14208
	ds_read_b32 v106, v141 offset:15824
	ds_read_b64 v[110:111], v142 offset:14528
	s_waitcnt lgkmcnt(13)
	v_pk_mul_f32 v[152:153], v[2:3], v[152:153]
	v_pk_mul_f32 v[164:165], v[2:3], v[164:165]
	v_pk_fma_f32 v[152:153], v[4:5], v[154:155], v[152:153]
	v_pk_fma_f32 v[164:165], v[4:5], v[166:167], v[164:165]
	v_add_f32_e32 v152, v152, v153
	v_add_f32_e32 v164, v164, v165
	v_pk_mul_f32 v[190:191], v[148:149], v[184:185] op_sel_hi:[1,0]
	v_add_f32_dpp v152, v152, v152 row_ror:8 row_mask:0xf bank_mask:0xf bound_ctrl:1
	v_add_f32_dpp v164, v164, v164 row_ror:8 row_mask:0xf bank_mask:0xf bound_ctrl:1
	v_pk_mul_f32 v[192:193], v[150:151], v[184:185] op_sel_hi:[1,0]
	v_add_f32_dpp v152, v152, v152 row_ror:4 row_mask:0xf bank_mask:0xf bound_ctrl:1
	v_add_f32_dpp v164, v164, v164 row_ror:4 row_mask:0xf bank_mask:0xf bound_ctrl:1
	v_pk_mul_f32 v[154:155], v[172:173], v[186:187] op_sel_hi:[1,0]
	v_add_f32_dpp v152, v152, v152 row_ror:2 row_mask:0xf bank_mask:0xf bound_ctrl:1
	v_add_f32_dpp v164, v164, v164 row_ror:2 row_mask:0xf bank_mask:0xf bound_ctrl:1
	v_pk_mul_f32 v[166:167], v[174:175], v[186:187] op_sel_hi:[1,0]
	v_add_f32_dpp v152, v152, v152 row_ror:1 row_mask:0xf bank_mask:0xf bound_ctrl:1
	v_add_f32_dpp v164, v164, v164 row_ror:1 row_mask:0xf bank_mask:0xf bound_ctrl:1
	v_pk_fma_f32 v[190:191], v[156:157], v[152:153], v[190:191] op_sel_hi:[1,0,1] neg_lo:[0,1,0] neg_hi:[0,1,0]
	v_pk_fma_f32 v[192:193], v[158:159], v[152:153], v[192:193] op_sel_hi:[1,0,1] neg_lo:[0,1,0] neg_hi:[0,1,0]
	v_fma_f32 v153, -v152, v188, v164
	v_pk_fma_f32 v[190:191], v[2:3], v[144:145], v[190:191]
	v_pk_fma_f32 v[192:193], v[4:5], v[146:147], v[192:193]
	v_fma_f32 v153, v184, v189, v153
	v_pk_mul_f32 v[160:161], v[190:191], v[160:161]
	v_pk_fma_f32 v[154:155], v[176:177], v[152:153], v[154:155] op_sel:[0,1,0] op_sel_hi:[1,1,1] neg_lo:[0,1,0] neg_hi:[0,1,0]
	v_pk_fma_f32 v[160:161], v[192:193], v[162:163], v[160:161]
	v_pk_fma_f32 v[166:167], v[178:179], v[152:153], v[166:167] op_sel:[0,1,0] op_sel_hi:[1,1,1] neg_lo:[0,1,0] neg_hi:[0,1,0]
	v_add_f32_e32 v107, v160, v161
	v_pk_fma_f32 v[2:3], v[190:191], v[168:169], v[154:155]
	v_pk_fma_f32 v[4:5], v[192:193], v[170:171], v[166:167]
	v_pk_mul_f32 v[180:181], v[2:3], v[180:181]
	v_pk_fma_f32 v[180:181], v[4:5], v[182:183], v[180:181]
	v_add_f32_e32 v109, v180, v181
	v_add_f32_dpp v185, v185, v185 row_ror:8 row_mask:0xf bank_mask:0xf bound_ctrl:1
	v_add_f32_dpp v187, v187, v187 row_ror:8 row_mask:0xf bank_mask:0xf bound_ctrl:1
	v_add_f32_dpp v107, v107, v107 row_ror:8 row_mask:0xf bank_mask:0xf bound_ctrl:1
	v_add_f32_dpp v109, v109, v109 row_ror:8 row_mask:0xf bank_mask:0xf bound_ctrl:1
	v_cndmask_b32_e64 v185, v185, v187, s[42:43]
	v_cndmask_b32_e64 v107, v107, v109, s[42:43]
	ds_read_b128 v[144:147], v140 offset:16160
	ds_read_b128 v[148:151], v140 offset:16416
	ds_read_b128 v[152:155], v140 offset:16672
	ds_read_b128 v[156:159], v140 offset:16928
	ds_read_b128 v[160:163], v140 offset:17184
	ds_read_b128 v[164:167], v140 offset:17504
	ds_read_b128 v[168:171], v140 offset:17776
	ds_read_b128 v[172:175], v140 offset:18032
	ds_read_b128 v[176:179], v140 offset:18544
	ds_read_b128 v[180:183], v140 offset:18800
	ds_read_b32 v184, v141 offset:17440
	ds_read_b32 v186, v141 offset:19056
	ds_read_b64 v[188:189], v142 offset:17760
	v_add_f32_dpp v185, v185, v185 row_half_mirror row_mask:0xf bank_mask:0xf bound_ctrl:1
	v_add_f32_dpp v107, v107, v107 row_half_mirror row_mask:0xf bank_mask:0xf bound_ctrl:1
	s_waitcnt lgkmcnt(13)
; __device__ __forceinline__ float row16_allsum(float x) { x = ROW_ROR_ADD(x, 8); x = ROW_ROR_ADD(x, 4); x = ROW_ROR_ADD(x, 2); x = ROW_ROR_ADD(x, 1); return x; }
; __device__ __forceinline__ float dot4(f32x4 a, f32x4 b) { return __builtin_fmaf(a[3], b[3], __builtin_fmaf(a[2], b[2], __builtin_fmaf(a[1], b[1], a[0] * b[0]))); }
; __device__ __forceinline__ void scan_phase(const Params& P, LAS unsigned char* lds, int tid, int wid, int lane) {
;     ...
;                 for (int t0 = 0; t0 < nsteps; t0 += 16) {
;                     float ykeep = 0.f;
; #pragma unroll
;                     for (int u = 0; u < 8; ++u) {
;                         SC_LOADP((u + 1) & 1, t0 + 2 * u + 2);
;                         const int s = u & 1;
;                         float dA = dot4(S, kk0[s]), dB = dot4(S, wk0[s]);
;                         dA = row16_allsum(dA); dB = row16_allsum(dB);
;                         const float sa0 = -dA;
;                         const f32x4 S0 = S * w0[s] + (b0[s] * sa0 + kh0[s] * v0[s]);
;                         const float sa1 = -(dB + sa0 * bk[s].x + v0[s] * bk[s].y);
;                         const f32x4 S1 = S0 * w1[s] + (b1[s] * sa1 + kh1[s] * v1[s]);
;                         float y0 = dot4(S0, r0[s]), y1 = dot4(S1, r1[s]);
;                         y0 = row16_allsum(y0); y1 = row16_allsum(y1);
;                         ykeep = (jq == 2 * u) ? y0 : ykeep; ykeep = (jq == 2 * u + 1) ? y1 : ykeep;
;                         S = S1;
;                     }
;                     yb[(t0 + jq) * 16 + il] = ykeep;
	v_cndmask_b32_e64 v185, v185, v107, s[44:45]
	v_pk_mul_f32 v[42:43], v[2:3], v[42:43]
	v_pk_mul_f32 v[38:39], v[2:3], v[38:39]
	v_add_f32_dpp v185, v185, v185 quad_perm:[1,0,3,2] row_mask:0xf bank_mask:0xf bound_ctrl:1
	v_pk_fma_f32 v[42:43], v[4:5], v[44:45], v[42:43]
	v_pk_fma_f32 v[38:39], v[4:5], v[40:41], v[38:39]
	v_add_f32_dpp v185, v185, v185 quad_perm:[2,3,0,1] row_mask:0xf bank_mask:0xf bound_ctrl:1
	v_add_f32_e32 v42, v42, v43
	v_add_f32_e32 v38, v38, v39
	v_cndmask_b32_e64 v143, v143, v185, s[48:49]
	v_pk_mul_f32 v[190:191], v[22:23], v[108:109] op_sel_hi:[1,0]
	v_add_f32_dpp v42, v42, v42 row_ror:8 row_mask:0xf bank_mask:0xf bound_ctrl:1
	v_add_f32_dpp v38, v38, v38 row_ror:8 row_mask:0xf bank_mask:0xf bound_ctrl:1
	v_pk_mul_f32 v[192:193], v[24:25], v[108:109] op_sel_hi:[1,0]
	v_add_f32_dpp v42, v42, v42 row_ror:4 row_mask:0xf bank_mask:0xf bound_ctrl:1
	v_add_f32_dpp v38, v38, v38 row_ror:4 row_mask:0xf bank_mask:0xf bound_ctrl:1
	v_pk_mul_f32 v[44:45], v[26:27], v[106:107] op_sel_hi:[1,0]
	v_add_f32_dpp v42, v42, v42 row_ror:2 row_mask:0xf bank_mask:0xf bound_ctrl:1
	v_add_f32_dpp v38, v38, v38 row_ror:2 row_mask:0xf bank_mask:0xf bound_ctrl:1
	v_pk_mul_f32 v[40:41], v[28:29], v[106:107] op_sel_hi:[1,0]
	v_add_f32_dpp v42, v42, v42 row_ror:1 row_mask:0xf bank_mask:0xf bound_ctrl:1
	v_add_f32_dpp v38, v38, v38 row_ror:1 row_mask:0xf bank_mask:0xf bound_ctrl:1
	v_pk_fma_f32 v[190:191], v[34:35], v[42:43], v[190:191] op_sel_hi:[1,0,1] neg_lo:[0,1,0] neg_hi:[0,1,0]
	v_pk_fma_f32 v[192:193], v[36:37], v[42:43], v[192:193] op_sel_hi:[1,0,1] neg_lo:[0,1,0] neg_hi:[0,1,0]
	v_fma_f32 v43, -v42, v110, v38
	v_pk_fma_f32 v[190:191], v[2:3], v[14:15], v[190:191]
	v_pk_fma_f32 v[192:193], v[4:5], v[16:17], v[192:193]
	v_fma_f32 v43, v108, v111, v43
	v_pk_mul_f32 v[6:7], v[190:191], v[6:7]
	v_pk_fma_f32 v[44:45], v[30:31], v[42:43], v[44:45] op_sel:[0,1,0] op_sel_hi:[1,1,1] neg_lo:[0,1,0] neg_hi:[0,1,0]
	v_pk_fma_f32 v[6:7], v[192:193], v[8:9], v[6:7]
	v_pk_fma_f32 v[40:41], v[32:33], v[42:43], v[40:41] op_sel:[0,1,0] op_sel_hi:[1,1,1] neg_lo:[0,1,0] neg_hi:[0,1,0]
	v_add_f32_e32 v185, v6, v7
	v_pk_fma_f32 v[2:3], v[190:191], v[18:19], v[44:45]
	v_pk_fma_f32 v[4:5], v[192:193], v[20:21], v[40:41]
	v_pk_mul_f32 v[10:11], v[2:3], v[10:11]
	v_pk_fma_f32 v[10:11], v[4:5], v[12:13], v[10:11]
	v_add_f32_e32 v187, v10, v11
	ds_read_b128 v[14:17], v140 offset:19392
	ds_read_b128 v[22:25], v140 offset:19648
	ds_read_b128 v[42:45], v140 offset:19904
	ds_read_b128 v[34:37], v140 offset:20160
	ds_read_b128 v[6:9], v140 offset:20416
	ds_read_b128 v[38:41], v140 offset:20736
	ds_read_b128 v[18:21], v140 offset:21008
	ds_read_b128 v[26:29], v140 offset:21264
	ds_read_b128 v[30:33], v140 offset:21776
	ds_read_b128 v[10:13], v140 offset:22032
	ds_read_b32 v108, v141 offset:20672
	ds_read_b32 v106, v141 offset:22288
	ds_read_b64 v[110:111], v142 offset:20992
	s_waitcnt lgkmcnt(13)
	v_pk_mul_f32 v[152:153], v[2:3], v[152:153]
	v_pk_mul_f32 v[164:165], v[2:3], v[164:165]
	v_pk_fma_f32 v[152:153], v[4:5], v[154:155], v[152:153]
	v_pk_fma_f32 v[164:165], v[4:5], v[166:167], v[164:165]
	v_add_f32_e32 v152, v152, v153
	v_add_f32_e32 v164, v164, v165
	v_pk_mul_f32 v[190:191], v[148:149], v[184:185] op_sel_hi:[1,0]
	v_add_f32_dpp v152, v152, v152 row_ror:8 row_mask:0xf bank_mask:0xf bound_ctrl:1
	v_add_f32_dpp v164, v164, v164 row_ror:8 row_mask:0xf bank_mask:0xf bound_ctrl:1
	v_pk_mul_f32 v[192:193], v[150:151], v[184:185] op_sel_hi:[1,0]
	v_add_f32_dpp v152, v152, v152 row_ror:4 row_mask:0xf bank_mask:0xf bound_ctrl:1
	v_add_f32_dpp v164, v164, v164 row_ror:4 row_mask:0xf bank_mask:0xf bound_ctrl:1
	v_pk_mul_f32 v[154:155], v[172:173], v[186:187] op_sel_hi:[1,0]
	v_add_f32_dpp v152, v152, v152 row_ror:2 row_mask:0xf bank_mask:0xf bound_ctrl:1
	v_add_f32_dpp v164, v164, v164 row_ror:2 row_mask:0xf bank_mask:0xf bound_ctrl:1
	v_pk_mul_f32 v[166:167], v[174:175], v[186:187] op_sel_hi:[1,0]
	v_add_f32_dpp v152, v152, v152 row_ror:1 row_mask:0xf bank_mask:0xf bound_ctrl:1
	v_add_f32_dpp v164, v164, v164 row_ror:1 row_mask:0xf bank_mask:0xf bound_ctrl:1
	v_pk_fma_f32 v[190:191], v[156:157], v[152:153], v[190:191] op_sel_hi:[1,0,1] neg_lo:[0,1,0] neg_hi:[0,1,0]
	v_pk_fma_f32 v[192:193], v[158:159], v[152:153], v[192:193] op_sel_hi:[1,0,1] neg_lo:[0,1,0] neg_hi:[0,1,0]
	v_fma_f32 v153, -v152, v188, v164
	v_pk_fma_f32 v[190:191], v[2:3], v[144:145], v[190:191]
	v_pk_fma_f32 v[192:193], v[4:5], v[146:147], v[192:193]
	v_fma_f32 v153, v184, v189, v153
	v_pk_mul_f32 v[160:161], v[190:191], v[160:161]
	v_pk_fma_f32 v[154:155], v[176:177], v[152:153], v[154:155] op_sel:[0,1,0] op_sel_hi:[1,1,1] neg_lo:[0,1,0] neg_hi:[0,1,0]
	v_pk_fma_f32 v[160:161], v[192:193], v[162:163], v[160:161]
	v_pk_fma_f32 v[166:167], v[178:179], v[152:153], v[166:167] op_sel:[0,1,0] op_sel_hi:[1,1,1] neg_lo:[0,1,0] neg_hi:[0,1,0]
	v_add_f32_e32 v107, v160, v161
	v_pk_fma_f32 v[2:3], v[190:191], v[168:169], v[154:155]
	v_pk_fma_f32 v[4:5], v[192:193], v[170:171], v[166:167]
	v_pk_mul_f32 v[180:181], v[2:3], v[180:181]
	v_pk_fma_f32 v[180:181], v[4:5], v[182:183], v[180:181]
	v_add_f32_e32 v109, v180, v181
	v_add_f32_dpp v185, v185, v185 row_ror:8 row_mask:0xf bank_mask:0xf bound_ctrl:1
	v_add_f32_dpp v187, v187, v187 row_ror:8 row_mask:0xf bank_mask:0xf bound_ctrl:1
	v_add_f32_dpp v107, v107, v107 row_ror:8 row_mask:0xf bank_mask:0xf bound_ctrl:1
	v_add_f32_dpp v109, v109, v109 row_ror:8 row_mask:0xf bank_mask:0xf bound_ctrl:1
	v_cndmask_b32_e64 v185, v185, v187, s[42:43]
	v_cndmask_b32_e64 v107, v107, v109, s[42:43]
	ds_read_b128 v[144:147], v140 offset:22624
	ds_read_b128 v[148:151], v140 offset:22880
	ds_read_b128 v[152:155], v140 offset:23136
	ds_read_b128 v[156:159], v140 offset:23392
	ds_read_b128 v[160:163], v140 offset:23648
	ds_read_b128 v[164:167], v140 offset:23968
	ds_read_b128 v[168:171], v140 offset:24240
	ds_read_b128 v[172:175], v140 offset:24496
	ds_read_b128 v[176:179], v140 offset:25008
	ds_read_b128 v[180:183], v140 offset:25264
	ds_read_b32 v184, v141 offset:23904
	ds_read_b32 v186, v141 offset:25520
	ds_read_b64 v[188:189], v142 offset:24224
	v_add_f32_dpp v185, v185, v185 row_half_mirror row_mask:0xf bank_mask:0xf bound_ctrl:1
	v_add_f32_dpp v107, v107, v107 row_half_mirror row_mask:0xf bank_mask:0xf bound_ctrl:1
	s_waitcnt lgkmcnt(13)
; __device__ __forceinline__ float row16_allsum(float x) { x = ROW_ROR_ADD(x, 8); x = ROW_ROR_ADD(x, 4); x = ROW_ROR_ADD(x, 2); x = ROW_ROR_ADD(x, 1); return x; }
; __device__ __forceinline__ float dot4(f32x4 a, f32x4 b) { return __builtin_fmaf(a[3], b[3], __builtin_fmaf(a[2], b[2], __builtin_fmaf(a[1], b[1], a[0] * b[0]))); }
; __device__ __forceinline__ void scan_phase(const Params& P, LAS unsigned char* lds, int tid, int wid, int lane) {
;     ...
;                 for (int t0 = 0; t0 < nsteps; t0 += 16) {
;                     float ykeep = 0.f;
; #pragma unroll
;                     for (int u = 0; u < 8; ++u) {
;                         SC_LOADP((u + 1) & 1, t0 + 2 * u + 2);
;                         const int s = u & 1;
;                         float dA = dot4(S, kk0[s]), dB = dot4(S, wk0[s]);
;                         dA = row16_allsum(dA); dB = row16_allsum(dB);
;                         const float sa0 = -dA;
;                         const f32x4 S0 = S * w0[s] + (b0[s] * sa0 + kh0[s] * v0[s]);
;                         const float sa1 = -(dB + sa0 * bk[s].x + v0[s] * bk[s].y);
;                         const f32x4 S1 = S0 * w1[s] + (b1[s] * sa1 + kh1[s] * v1[s]);
;                         float y0 = dot4(S0, r0[s]), y1 = dot4(S1, r1[s]);
;                         y0 = row16_allsum(y0); y1 = row16_allsum(y1);
;                         ykeep = (jq == 2 * u) ? y0 : ykeep; ykeep = (jq == 2 * u + 1) ? y1 : ykeep;
;                         S = S1;
;                     }
;                     yb[(t0 + jq) * 16 + il] = ykeep;
;                 }
	v_cndmask_b32_e64 v185, v185, v107, s[44:45]
	v_pk_mul_f32 v[42:43], v[2:3], v[42:43]
	v_pk_mul_f32 v[38:39], v[2:3], v[38:39]
	v_add_f32_dpp v185, v185, v185 quad_perm:[1,0,3,2] row_mask:0xf bank_mask:0xf bound_ctrl:1
	v_pk_fma_f32 v[42:43], v[4:5], v[44:45], v[42:43]
	v_pk_fma_f32 v[38:39], v[4:5], v[40:41], v[38:39]
	v_add_f32_dpp v185, v185, v185 quad_perm:[2,3,0,1] row_mask:0xf bank_mask:0xf bound_ctrl:1
	v_add_f32_e32 v42, v42, v43
	v_add_f32_e32 v38, v38, v39
	v_cndmask_b32_e64 v143, v143, v185, s[50:51]
	v_pk_mul_f32 v[190:191], v[22:23], v[108:109] op_sel_hi:[1,0]
	v_add_f32_dpp v42, v42, v42 row_ror:8 row_mask:0xf bank_mask:0xf bound_ctrl:1
	v_add_f32_dpp v38, v38, v38 row_ror:8 row_mask:0xf bank_mask:0xf bound_ctrl:1
	v_pk_mul_f32 v[192:193], v[24:25], v[108:109] op_sel_hi:[1,0]
	v_add_f32_dpp v42, v42, v42 row_ror:4 row_mask:0xf bank_mask:0xf bound_ctrl:1
	v_add_f32_dpp v38, v38, v38 row_ror:4 row_mask:0xf bank_mask:0xf bound_ctrl:1
	v_pk_mul_f32 v[44:45], v[26:27], v[106:107] op_sel_hi:[1,0]
	v_add_f32_dpp v42, v42, v42 row_ror:2 row_mask:0xf bank_mask:0xf bound_ctrl:1
	v_add_f32_dpp v38, v38, v38 row_ror:2 row_mask:0xf bank_mask:0xf bound_ctrl:1
	v_pk_mul_f32 v[40:41], v[28:29], v[106:107] op_sel_hi:[1,0]
	v_add_f32_dpp v42, v42, v42 row_ror:1 row_mask:0xf bank_mask:0xf bound_ctrl:1
	v_add_f32_dpp v38, v38, v38 row_ror:1 row_mask:0xf bank_mask:0xf bound_ctrl:1
	v_pk_fma_f32 v[190:191], v[34:35], v[42:43], v[190:191] op_sel_hi:[1,0,1] neg_lo:[0,1,0] neg_hi:[0,1,0]
	v_pk_fma_f32 v[192:193], v[36:37], v[42:43], v[192:193] op_sel_hi:[1,0,1] neg_lo:[0,1,0] neg_hi:[0,1,0]
	v_fma_f32 v43, -v42, v110, v38
	v_pk_fma_f32 v[190:191], v[2:3], v[14:15], v[190:191]
	v_pk_fma_f32 v[192:193], v[4:5], v[16:17], v[192:193]
	v_fma_f32 v43, v108, v111, v43
	v_pk_mul_f32 v[6:7], v[190:191], v[6:7]
	v_pk_fma_f32 v[44:45], v[30:31], v[42:43], v[44:45] op_sel:[0,1,0] op_sel_hi:[1,1,1] neg_lo:[0,1,0] neg_hi:[0,1,0]
	v_pk_fma_f32 v[6:7], v[192:193], v[8:9], v[6:7]
	v_pk_fma_f32 v[40:41], v[32:33], v[42:43], v[40:41] op_sel:[0,1,0] op_sel_hi:[1,1,1] neg_lo:[0,1,0] neg_hi:[0,1,0]
	v_add_f32_e32 v185, v6, v7
	v_pk_fma_f32 v[2:3], v[190:191], v[18:19], v[44:45]
	v_pk_fma_f32 v[4:5], v[192:193], v[20:21], v[40:41]
	v_pk_mul_f32 v[10:11], v[2:3], v[10:11]
	v_pk_fma_f32 v[10:11], v[4:5], v[12:13], v[10:11]
	v_add_f32_e32 v187, v10, v11
	ds_read_b128 v[14:17], v140 offset:25856
	ds_read_b128 v[22:25], v140 offset:26112
	ds_read_b128 v[42:45], v140 offset:26368
	ds_read_b128 v[34:37], v140 offset:26624
	ds_read_b128 v[6:9], v140 offset:26880
	ds_read_b128 v[38:41], v140 offset:27200
	ds_read_b128 v[18:21], v140 offset:27472
	ds_read_b128 v[26:29], v140 offset:27728
	ds_read_b128 v[30:33], v140 offset:28240
	ds_read_b128 v[10:13], v140 offset:28496
	ds_read_b32 v108, v141 offset:27136
	ds_read_b32 v106, v141 offset:28752
	ds_read_b64 v[110:111], v142 offset:27456
	s_waitcnt lgkmcnt(13)
	v_pk_mul_f32 v[152:153], v[2:3], v[152:153]
	v_pk_mul_f32 v[164:165], v[2:3], v[164:165]
	v_pk_fma_f32 v[152:153], v[4:5], v[154:155], v[152:153]
	v_pk_fma_f32 v[164:165], v[4:5], v[166:167], v[164:165]
	v_add_f32_e32 v152, v152, v153
	v_add_f32_e32 v164, v164, v165
	v_pk_mul_f32 v[190:191], v[148:149], v[184:185] op_sel_hi:[1,0]
	v_add_f32_dpp v152, v152, v152 row_ror:8 row_mask:0xf bank_mask:0xf bound_ctrl:1
	v_add_f32_dpp v164, v164, v164 row_ror:8 row_mask:0xf bank_mask:0xf bound_ctrl:1
	v_pk_mul_f32 v[192:193], v[150:151], v[184:185] op_sel_hi:[1,0]
	v_add_f32_dpp v152, v152, v152 row_ror:4 row_mask:0xf bank_mask:0xf bound_ctrl:1
	v_add_f32_dpp v164, v164, v164 row_ror:4 row_mask:0xf bank_mask:0xf bound_ctrl:1
	v_pk_mul_f32 v[154:155], v[172:173], v[186:187] op_sel_hi:[1,0]
	v_add_f32_dpp v152, v152, v152 row_ror:2 row_mask:0xf bank_mask:0xf bound_ctrl:1
	v_add_f32_dpp v164, v164, v164 row_ror:2 row_mask:0xf bank_mask:0xf bound_ctrl:1
	v_pk_mul_f32 v[166:167], v[174:175], v[186:187] op_sel_hi:[1,0]
	v_add_f32_dpp v152, v152, v152 row_ror:1 row_mask:0xf bank_mask:0xf bound_ctrl:1
	v_add_f32_dpp v164, v164, v164 row_ror:1 row_mask:0xf bank_mask:0xf bound_ctrl:1
	v_pk_fma_f32 v[190:191], v[156:157], v[152:153], v[190:191] op_sel_hi:[1,0,1] neg_lo:[0,1,0] neg_hi:[0,1,0]
	v_pk_fma_f32 v[192:193], v[158:159], v[152:153], v[192:193] op_sel_hi:[1,0,1] neg_lo:[0,1,0] neg_hi:[0,1,0]
	v_fma_f32 v153, -v152, v188, v164
	v_pk_fma_f32 v[190:191], v[2:3], v[144:145], v[190:191]
	v_pk_fma_f32 v[192:193], v[4:5], v[146:147], v[192:193]
	v_fma_f32 v153, v184, v189, v153
	v_pk_mul_f32 v[160:161], v[190:191], v[160:161]
	v_pk_fma_f32 v[154:155], v[176:177], v[152:153], v[154:155] op_sel:[0,1,0] op_sel_hi:[1,1,1] neg_lo:[0,1,0] neg_hi:[0,1,0]
	v_pk_fma_f32 v[160:161], v[192:193], v[162:163], v[160:161]
	v_pk_fma_f32 v[166:167], v[178:179], v[152:153], v[166:167] op_sel:[0,1,0] op_sel_hi:[1,1,1] neg_lo:[0,1,0] neg_hi:[0,1,0]
	v_add_f32_e32 v107, v160, v161
	v_pk_fma_f32 v[2:3], v[190:191], v[168:169], v[154:155]
	v_pk_fma_f32 v[4:5], v[192:193], v[170:171], v[166:167]
	v_pk_mul_f32 v[180:181], v[2:3], v[180:181]
	v_pk_fma_f32 v[180:181], v[4:5], v[182:183], v[180:181]
	v_add_f32_e32 v109, v180, v181
	v_add_f32_dpp v185, v185, v185 row_ror:8 row_mask:0xf bank_mask:0xf bound_ctrl:1
	v_add_f32_dpp v187, v187, v187 row_ror:8 row_mask:0xf bank_mask:0xf bound_ctrl:1
	v_add_f32_dpp v107, v107, v107 row_ror:8 row_mask:0xf bank_mask:0xf bound_ctrl:1
	v_add_f32_dpp v109, v109, v109 row_ror:8 row_mask:0xf bank_mask:0xf bound_ctrl:1
	v_cndmask_b32_e64 v185, v185, v187, s[42:43]
	v_cndmask_b32_e64 v107, v107, v109, s[42:43]
	s_and_b64 vcc, s[8:9], s[12:13]
	s_mov_b64 s[12:13], 0
	v_add_f32_dpp v185, v185, v185 row_half_mirror row_mask:0xf bank_mask:0xf bound_ctrl:1
	v_add_f32_dpp v107, v107, v107 row_half_mirror row_mask:0xf bank_mask:0xf bound_ctrl:1
	v_lshl_add_u32 v193, s37, 6, v255
	v_cndmask_b32_e64 v185, v185, v107, s[44:45]
	s_andn2_b64 vcc, exec, vcc
	v_add_u32_e32 v193, v193, v65
	v_add_f32_dpp v185, v185, v185 quad_perm:[1,0,3,2] row_mask:0xf bank_mask:0xf bound_ctrl:1
	s_mov_b32 s37, 16
	s_nop 0
	v_add_f32_dpp v185, v185, v185 quad_perm:[2,3,0,1] row_mask:0xf bank_mask:0xf bound_ctrl:1
	v_cndmask_b32_e64 v143, v143, v185, s[52:53]
	ds_write_b32 v193, v143
	s_cbranch_vccz .LBB0_881
	s_branch .LBB0_859

; __global__ void __launch_bounds__(NTHREADS, 2) mega(Params P, int ph_lo, int ph_hi) {
	.amdhsa_kernel _Z4mega6Paramsii
		.amdhsa_group_segment_fixed_size 0
		.amdhsa_private_segment_fixed_size 0
		.amdhsa_kernarg_size 504
		.amdhsa_user_sgpr_count 2
		.amdhsa_user_sgpr_dispatch_ptr 0
		.amdhsa_user_sgpr_queue_ptr 0
		.amdhsa_user_sgpr_kernarg_segment_ptr 1
		.amdhsa_user_sgpr_dispatch_id 0
		.amdhsa_user_sgpr_kernarg_preload_length 0
		.amdhsa_user_sgpr_kernarg_preload_offset 0
		.amdhsa_user_sgpr_private_segment_size 0
		.amdhsa_uses_dynamic_stack 0
		.amdhsa_enable_private_segment 0
		.amdhsa_system_sgpr_workgroup_id_x 1
		.amdhsa_system_sgpr_workgroup_id_y 0
		.amdhsa_system_sgpr_workgroup_id_z 0
		.amdhsa_system_sgpr_workgroup_info 0
		.amdhsa_system_vgpr_workitem_id 2
		.amdhsa_next_free_vgpr 256
		.amdhsa_next_free_sgpr 102
		.amdhsa_accum_offset 256
		.amdhsa_reserve_vcc 1
		.amdhsa_float_round_mode_32 0
		.amdhsa_float_round_mode_16_64 0
		.amdhsa_float_denorm_mode_32 3
		.amdhsa_float_denorm_mode_16_64 3
		.amdhsa_dx10_clamp 1
		.amdhsa_ieee_mode 1
		.amdhsa_fp16_overflow 0
		.amdhsa_tg_split 0
		.amdhsa_exception_fp_ieee_invalid_op 0
		.amdhsa_exception_fp_denorm_src 0
		.amdhsa_exception_fp_ieee_div_zero 0
		.amdhsa_exception_fp_ieee_overflow 0
		.amdhsa_exception_fp_ieee_underflow 0
		.amdhsa_exception_fp_ieee_inexact 0
		.amdhsa_exception_int_div_zero 0
	.end_amdhsa_kernel

; __global__ void __launch_bounds__(NTHREADS, 2) mega(Params P, int ph_lo, int ph_hi) {
amdhsa.kernels:
  - .agpr_count:     0
    .args:
      - .offset:         0
        .size:           240
        .value_kind:     by_value
      - .offset:         240
        .size:           4
        .value_kind:     by_value
      - .offset:         244
        .size:           4
        .value_kind:     by_value
      - .offset:         248
        .size:           4
        .value_kind:     hidden_block_count_x
      - .offset:         252
        .size:           4
        .value_kind:     hidden_block_count_y
      - .offset:         256
        .size:           4
        .value_kind:     hidden_block_count_z
      - .offset:         260
        .size:           2
        .value_kind:     hidden_group_size_x
      - .offset:         262
        .size:           2
        .value_kind:     hidden_group_size_y
      - .offset:         264
        .size:           2
        .value_kind:     hidden_group_size_z
      - .offset:         266
        .size:           2
        .value_kind:     hidden_remainder_x
      - .offset:         268
        .size:           2
        .value_kind:     hidden_remainder_y
      - .offset:         270
        .size:           2
        .value_kind:     hidden_remainder_z
      - .offset:         288
        .size:           8
        .value_kind:     hidden_global_offset_x
      - .offset:         296
        .size:           8
        .value_kind:     hidden_global_offset_y
      - .offset:         304
        .size:           8
        .value_kind:     hidden_global_offset_z
      - .offset:         312
        .size:           2
        .value_kind:     hidden_grid_dims
      - .offset:         336
        .size:           8
        .value_kind:     hidden_multigrid_sync_arg
      - .offset:         368
        .size:           4
        .value_kind:     hidden_dynamic_lds_size
    .group_segment_fixed_size: 0
    .kernarg_segment_align: 8
    .kernarg_segment_size: 504
    .language:       OpenCL C
    .language_version:
      - 2
      - 0
    .max_flat_workgroup_size: 512
    .name:           _Z4mega6Paramsii
    .private_segment_fixed_size: 0
    .sgpr_count:     108
    .sgpr_spill_count: 42
    .symbol:         _Z4mega6Paramsii.kd
    .uniform_work_group_size: 1
    .uses_dynamic_stack: false
    .vgpr_count:     256
    .vgpr_spill_count: 0
    .wavefront_size: 64
